# K-loop load sections: the m0-to-LDS-DMA wait state is filled by one of the section's ds_reads instead of an s_nop (about 10 nops per iteration removed)
# baseline (speedup 1.0000x reference)
.LBB0_288:
	s_add_u32 s30, s28, 0xfffc0080
	s_addc_u32 s31, s29, -1
	s_add_i32 s56, 0, 0x10000
	s_cmp_eq_u32 s55, 12
	s_cselect_b32 s35, s21, s31
	s_cselect_b32 s34, s36, s30
	s_cselect_b32 s31, s19, s39
	s_cselect_b32 s30, s37, s38
	s_add_i32 s58, 0, 0x14000
	v_add_u32_e32 v166, s56, v147
	v_add_u32_e32 v182, s58, v147
	ds_read_b128 v[142:145], v166
	ds_read_b128 v[158:161], v166 offset:1024
	ds_read_b128 v[162:165], v166 offset:2048
	ds_read_b128 v[166:169], v166 offset:3072
	ds_read_b128 v[170:173], v182
	ds_read_b128 v[174:177], v182 offset:1024
	ds_read_b128 v[178:181], v182 offset:2048
	ds_read_b128 v[182:185], v182 offset:3072
	s_add_i32 m0, s44, 0xc000
	ds_read_b128 v[186:189], v157
	ds_read_b128 v[190:193], v157 offset:1024
	ds_read_b128 v[194:197], v157 offset:2048
	ds_read_b128 v[198:201], v157 offset:3072
	ds_read_b128 v[202:205], v157 offset:4096
	ds_read_b128 v[206:209], v157 offset:5120
	ds_read_b128 v[220:223], v157 offset:6144
	global_load_lds_dwordx4 v140, s[28:29]
	s_add_i32 m0, s44, 0xe000
	ds_read_b128 v[236:239], v157 offset:7168
	global_load_lds_dwordx4 v138, s[28:29]
	s_branch .Lpadj_4
	s_nop 0
	s_nop 0
	s_nop 0
	s_nop 0
	s_nop 0
	s_nop 0
	s_nop 0
	s_nop 0
	s_nop 0
	s_nop 0
	s_nop 0
	s_nop 0
	s_nop 0
.Lpadj_4:
	s_waitcnt vmcnt(8)
	s_waitcnt lgkmcnt(0)
	s_barrier
	v_mfma_f32_16x16x32_bf16 v[126:129], v[142:145], v[186:189], v[126:129]
	v_mfma_f32_16x16x32_bf16 v[122:125], v[162:165], v[186:189], v[122:125]
	v_mfma_f32_16x16x32_bf16 v[110:113], v[142:145], v[194:197], v[110:113]
	v_mfma_f32_16x16x32_bf16 v[106:109], v[162:165], v[194:197], v[106:109]
	v_mfma_f32_16x16x32_bf16 v[94:97], v[142:145], v[202:205], v[94:97]
	v_mfma_f32_16x16x32_bf16 v[90:93], v[162:165], v[202:205], v[90:93]
	v_mfma_f32_16x16x32_bf16 v[78:81], v[142:145], v[220:223], v[78:81]
	v_mfma_f32_16x16x32_bf16 v[74:77], v[162:165], v[220:223], v[74:77]
	v_mfma_f32_16x16x32_bf16 v[126:129], v[158:161], v[190:193], v[126:129]
	v_mfma_f32_16x16x32_bf16 v[122:125], v[166:169], v[190:193], v[122:125]
	v_mfma_f32_16x16x32_bf16 v[110:113], v[158:161], v[198:201], v[110:113]
	v_mfma_f32_16x16x32_bf16 v[106:109], v[166:169], v[198:201], v[106:109]
	v_mfma_f32_16x16x32_bf16 v[94:97], v[158:161], v[206:209], v[94:97]
	v_mfma_f32_16x16x32_bf16 v[90:93], v[166:169], v[206:209], v[90:93]
	v_mfma_f32_16x16x32_bf16 v[78:81], v[158:161], v[236:239], v[78:81]
	v_mfma_f32_16x16x32_bf16 v[74:77], v[166:169], v[236:239], v[74:77]
	v_mfma_f32_16x16x32_bf16 v[118:121], v[170:173], v[186:189], v[118:121]
	v_mfma_f32_16x16x32_bf16 v[114:117], v[178:181], v[186:189], v[114:117]
	v_mfma_f32_16x16x32_bf16 v[102:105], v[170:173], v[194:197], v[102:105]
	v_mfma_f32_16x16x32_bf16 v[98:101], v[178:181], v[194:197], v[98:101]
	v_mfma_f32_16x16x32_bf16 v[86:89], v[170:173], v[202:205], v[86:89]
	v_mfma_f32_16x16x32_bf16 v[82:85], v[178:181], v[202:205], v[82:85]
	v_mfma_f32_16x16x32_bf16 v[70:73], v[170:173], v[220:223], v[70:73]
	v_mfma_f32_16x16x32_bf16 v[66:69], v[178:181], v[220:223], v[66:69]
	v_mfma_f32_16x16x32_bf16 v[118:121], v[174:177], v[190:193], v[118:121]
	v_mfma_f32_16x16x32_bf16 v[114:117], v[182:185], v[190:193], v[114:117]
	v_mfma_f32_16x16x32_bf16 v[102:105], v[174:177], v[198:201], v[102:105]
	v_mfma_f32_16x16x32_bf16 v[98:101], v[182:185], v[198:201], v[98:101]
	v_mfma_f32_16x16x32_bf16 v[86:89], v[174:177], v[206:209], v[86:89]
	v_mfma_f32_16x16x32_bf16 v[82:85], v[182:185], v[206:209], v[82:85]
	v_mfma_f32_16x16x32_bf16 v[70:73], v[174:177], v[236:239], v[70:73]
	v_mfma_f32_16x16x32_bf16 v[66:69], v[182:185], v[236:239], v[66:69]
	s_barrier
	s_add_i32 s56, s56, s27
	s_mov_b32 m0, s56
	ds_read_b128 v[186:189], v157 offset:16384
	ds_read_b128 v[190:193], v157 offset:17408
	ds_read_b128 v[194:197], v157 offset:18432
	ds_read_b128 v[198:201], v157 offset:19456
	global_load_lds_dwordx4 v132, s[30:31]
	s_add_i32 m0, s56, 0x2000
	s_add_u32 s56, s30, 0x40000
	s_addc_u32 s57, s31, 0
	s_add_i32 s58, s58, s27
	global_load_lds_dwordx4 v136, s[30:31]
	s_mov_b32 m0, s58
	ds_read_b128 v[202:205], v157 offset:20480
	global_load_lds_dwordx4 v132, s[56:57]
	s_add_i32 m0, s58, 0x2000
	ds_read_b128 v[206:209], v157 offset:21504
	global_load_lds_dwordx4 v136, s[56:57]
	s_mov_b32 m0, s44
	ds_read_b128 v[220:223], v157 offset:22528
	global_load_lds_dwordx4 v130, s[34:35]
	s_mov_b32 m0, s45
	ds_read_b128 v[236:239], v157 offset:23552
	global_load_lds_dwordx4 v134, s[34:35]
	s_nop 0
	s_nop 0
	s_nop 0
	s_waitcnt vmcnt(8)
	s_waitcnt lgkmcnt(0)
	s_barrier
	v_mfma_f32_16x16x32_bf16 v[62:65], v[142:145], v[186:189], v[62:65]
	v_mfma_f32_16x16x32_bf16 v[58:61], v[162:165], v[186:189], v[58:61]
	v_mfma_f32_16x16x32_bf16 v[46:49], v[142:145], v[194:197], v[46:49]
	v_mfma_f32_16x16x32_bf16 v[42:45], v[162:165], v[194:197], v[42:45]
	v_mfma_f32_16x16x32_bf16 v[30:33], v[142:145], v[202:205], v[30:33]
	v_mfma_f32_16x16x32_bf16 v[26:29], v[162:165], v[202:205], v[26:29]
	v_mfma_f32_16x16x32_bf16 v[14:17], v[142:145], v[220:223], v[14:17]
	v_mfma_f32_16x16x32_bf16 v[10:13], v[162:165], v[220:223], v[10:13]
	v_mfma_f32_16x16x32_bf16 v[62:65], v[158:161], v[190:193], v[62:65]
	v_mfma_f32_16x16x32_bf16 v[58:61], v[166:169], v[190:193], v[58:61]
	v_mfma_f32_16x16x32_bf16 v[46:49], v[158:161], v[198:201], v[46:49]
	v_mfma_f32_16x16x32_bf16 v[42:45], v[166:169], v[198:201], v[42:45]
	v_mfma_f32_16x16x32_bf16 v[30:33], v[158:161], v[206:209], v[30:33]
	v_mfma_f32_16x16x32_bf16 v[26:29], v[166:169], v[206:209], v[26:29]
	v_mfma_f32_16x16x32_bf16 v[14:17], v[158:161], v[236:239], v[14:17]
	v_mfma_f32_16x16x32_bf16 v[10:13], v[166:169], v[236:239], v[10:13]
	v_mfma_f32_16x16x32_bf16 v[54:57], v[170:173], v[186:189], v[54:57]
	v_mfma_f32_16x16x32_bf16 v[50:53], v[178:181], v[186:189], v[50:53]
	v_mfma_f32_16x16x32_bf16 v[38:41], v[170:173], v[194:197], v[38:41]
	v_mfma_f32_16x16x32_bf16 v[34:37], v[178:181], v[194:197], v[34:37]
	v_mfma_f32_16x16x32_bf16 v[22:25], v[170:173], v[202:205], v[22:25]
	v_mfma_f32_16x16x32_bf16 v[18:21], v[178:181], v[202:205], v[18:21]
	v_mfma_f32_16x16x32_bf16 v[6:9], v[170:173], v[220:223], v[6:9]
	v_mfma_f32_16x16x32_bf16 v[2:5], v[178:181], v[220:223], v[2:5]
	v_mfma_f32_16x16x32_bf16 v[54:57], v[174:177], v[190:193], v[54:57]
	v_mfma_f32_16x16x32_bf16 v[50:53], v[182:185], v[190:193], v[50:53]
	v_mfma_f32_16x16x32_bf16 v[38:41], v[174:177], v[198:201], v[38:41]
	v_mfma_f32_16x16x32_bf16 v[34:37], v[182:185], v[198:201], v[34:37]
	v_mfma_f32_16x16x32_bf16 v[22:25], v[174:177], v[206:209], v[22:25]
	v_mfma_f32_16x16x32_bf16 v[18:21], v[182:185], v[206:209], v[18:21]
	v_mfma_f32_16x16x32_bf16 v[6:9], v[174:177], v[236:239], v[6:9]
	v_mfma_f32_16x16x32_bf16 v[2:5], v[182:185], v[236:239], v[2:5]
	s_barrier
	s_add_i32 s56, 0, 0x18000
	s_add_i32 s57, 0, 0x1c000
	v_add_u32_e32 v166, s56, v147
	v_add_u32_e32 v182, s57, v147
	ds_read_b128 v[142:145], v166
	ds_read_b128 v[158:161], v166 offset:1024
	ds_read_b128 v[162:165], v166 offset:2048
	ds_read_b128 v[166:169], v166 offset:3072
	ds_read_b128 v[170:173], v182
	ds_read_b128 v[174:177], v182 offset:1024
	ds_read_b128 v[178:181], v182 offset:2048
	ds_read_b128 v[182:185], v182 offset:3072
	s_add_u32 s34, s34, 0x40000
	s_addc_u32 s35, s35, 0
	s_mov_b32 m0, s43
	ds_read_b128 v[186:189], v157 offset:32768
	ds_read_b128 v[190:193], v157 offset:33792
	ds_read_b128 v[194:197], v157 offset:34816
	ds_read_b128 v[198:201], v157 offset:35840
	ds_read_b128 v[202:205], v157 offset:36864
	ds_read_b128 v[206:209], v157 offset:37888
	ds_read_b128 v[220:223], v157 offset:38912
	global_load_lds_dwordx4 v130, s[34:35]
	s_mov_b32 m0, s46
	ds_read_b128 v[236:239], v157 offset:39936
	global_load_lds_dwordx4 v134, s[34:35]
	s_branch .Lpadj_5
	s_nop 0
	s_nop 0
	s_nop 0
	s_nop 0
	s_nop 0
	s_nop 0
	s_nop 0
	s_nop 0
	s_nop 0
	s_nop 0
	s_nop 0
	s_nop 0
.Lpadj_5:
	s_waitcnt vmcnt(8)
	s_waitcnt lgkmcnt(0)
	s_barrier
	v_mfma_f32_16x16x32_bf16 v[126:129], v[142:145], v[186:189], v[126:129]
	v_mfma_f32_16x16x32_bf16 v[122:125], v[162:165], v[186:189], v[122:125]
	v_mfma_f32_16x16x32_bf16 v[110:113], v[142:145], v[194:197], v[110:113]
	v_mfma_f32_16x16x32_bf16 v[106:109], v[162:165], v[194:197], v[106:109]
	v_mfma_f32_16x16x32_bf16 v[94:97], v[142:145], v[202:205], v[94:97]
	v_mfma_f32_16x16x32_bf16 v[90:93], v[162:165], v[202:205], v[90:93]
	v_mfma_f32_16x16x32_bf16 v[78:81], v[142:145], v[220:223], v[78:81]
	v_mfma_f32_16x16x32_bf16 v[74:77], v[162:165], v[220:223], v[74:77]
	v_mfma_f32_16x16x32_bf16 v[126:129], v[158:161], v[190:193], v[126:129]
	v_mfma_f32_16x16x32_bf16 v[122:125], v[166:169], v[190:193], v[122:125]
	v_mfma_f32_16x16x32_bf16 v[110:113], v[158:161], v[198:201], v[110:113]
	v_mfma_f32_16x16x32_bf16 v[106:109], v[166:169], v[198:201], v[106:109]
	v_mfma_f32_16x16x32_bf16 v[94:97], v[158:161], v[206:209], v[94:97]
	v_mfma_f32_16x16x32_bf16 v[90:93], v[166:169], v[206:209], v[90:93]
	v_mfma_f32_16x16x32_bf16 v[78:81], v[158:161], v[236:239], v[78:81]
	v_mfma_f32_16x16x32_bf16 v[74:77], v[166:169], v[236:239], v[74:77]
	v_mfma_f32_16x16x32_bf16 v[118:121], v[170:173], v[186:189], v[118:121]
	v_mfma_f32_16x16x32_bf16 v[114:117], v[178:181], v[186:189], v[114:117]
	v_mfma_f32_16x16x32_bf16 v[102:105], v[170:173], v[194:197], v[102:105]
	v_mfma_f32_16x16x32_bf16 v[98:101], v[178:181], v[194:197], v[98:101]
	v_mfma_f32_16x16x32_bf16 v[86:89], v[170:173], v[202:205], v[86:89]
	v_mfma_f32_16x16x32_bf16 v[82:85], v[178:181], v[202:205], v[82:85]
	v_mfma_f32_16x16x32_bf16 v[70:73], v[170:173], v[220:223], v[70:73]
	v_mfma_f32_16x16x32_bf16 v[66:69], v[178:181], v[220:223], v[66:69]
	v_mfma_f32_16x16x32_bf16 v[118:121], v[174:177], v[190:193], v[118:121]
	v_mfma_f32_16x16x32_bf16 v[114:117], v[182:185], v[190:193], v[114:117]
	v_mfma_f32_16x16x32_bf16 v[102:105], v[174:177], v[198:201], v[102:105]
	v_mfma_f32_16x16x32_bf16 v[98:101], v[182:185], v[198:201], v[98:101]
	v_mfma_f32_16x16x32_bf16 v[86:89], v[174:177], v[206:209], v[86:89]
	v_mfma_f32_16x16x32_bf16 v[82:85], v[182:185], v[206:209], v[82:85]
	v_mfma_f32_16x16x32_bf16 v[70:73], v[174:177], v[236:239], v[70:73]
	v_mfma_f32_16x16x32_bf16 v[66:69], v[182:185], v[236:239], v[66:69]
	s_barrier
	s_add_u32 s100, s34, 0xfffc0080
	s_addc_u32 s101, s35, -1
	s_add_u32 s30, s30, 0x80
	s_addc_u32 s31, s31, 0
	s_add_i32 s34, s56, s27
	s_mov_b32 m0, s34
	ds_read_b128 v[186:189], v157 offset:49152
	ds_read_b128 v[190:193], v157 offset:50176
	ds_read_b128 v[194:197], v157 offset:51200
	ds_read_b128 v[198:201], v157 offset:52224
	global_load_lds_dwordx4 v132, s[30:31]
	s_add_i32 m0, s34, 0x2000
	s_add_i32 s34, s57, s27
	global_load_lds_dwordx4 v136, s[30:31]
	s_add_u32 s30, s30, 0x40000
	s_addc_u32 s31, s31, 0
	s_mov_b32 m0, s34
	ds_read_b128 v[202:205], v157 offset:53248
	global_load_lds_dwordx4 v132, s[30:31]
	s_add_i32 m0, s34, 0x2000
	ds_read_b128 v[206:209], v157 offset:54272
	global_load_lds_dwordx4 v136, s[30:31]
	s_mov_b32 m0, s47
	ds_read_b128 v[220:223], v157 offset:55296
	global_load_lds_dwordx4 v130, s[100:101]
	s_mov_b32 m0, s48
	ds_read_b128 v[236:239], v157 offset:56320
	global_load_lds_dwordx4 v134, s[100:101]
	s_branch .Lpadj_6
	s_nop 0
	s_nop 0
	s_nop 0
	s_nop 0
	s_nop 0
	s_nop 0
	s_nop 0
	s_nop 0
	s_nop 0
	s_nop 0
	s_nop 0
	s_nop 0

.LBB0_363:
	s_add_u32 s34, s30, 0xfffc0080
	s_addc_u32 s35, s31, -1
	s_add_i32 s57, 0, 0x10000
	s_cmp_eq_u32 s56, 12
	s_cselect_b32 s37, s23, s35
	s_cselect_b32 s36, s39, s34
	v_add_u32_e32 v146, s57, v155
	s_cselect_b32 s35, s21, s43
	s_cselect_b32 s34, s40, s41
	s_add_i32 s60, 0, 0x14000
	ds_read_b128 v[142:145], v146
	ds_read_b128 v[168:171], v146 offset:1024
	ds_read_b128 v[172:175], v146 offset:2048
	ds_read_b128 v[176:179], v146 offset:3072
	v_add_u32_e32 v146, s60, v155
	ds_read_b128 v[180:183], v146
	ds_read_b128 v[184:187], v146 offset:1024
	ds_read_b128 v[188:191], v146 offset:2048
	ds_read_b128 v[192:195], v146 offset:3072
	s_add_i32 m0, s48, 0xc000
	ds_read_b128 v[196:199], v157
	ds_read_b128 v[200:203], v157 offset:1024
	ds_read_b128 v[204:207], v157 offset:2048
	ds_read_b128 v[220:223], v157 offset:3072
	ds_read_b128 v[236:239], v157 offset:4096
	ds_read_b128 v[240:243], v157 offset:5120
	ds_read_b128 v[244:247], v157 offset:6144
	global_load_lds_dwordx4 v140, s[30:31]
	s_add_i32 m0, s48, 0xe000
	ds_read_b128 v[248:251], v157 offset:7168
	global_load_lds_dwordx4 v138, s[30:31]
	s_branch .Lpadj_11
	s_nop 0
	s_nop 0
	s_nop 0
	s_nop 0
	s_nop 0
	s_nop 0
	s_nop 0
	s_nop 0
	s_nop 0
	s_nop 0
	s_nop 0
	s_nop 0
	s_nop 0
.Lpadj_11:
	s_waitcnt vmcnt(8)
	s_waitcnt lgkmcnt(0)
	s_barrier
	v_mfma_f32_16x16x32_bf16 v[126:129], v[142:145], v[196:199], v[126:129]
	v_mfma_f32_16x16x32_bf16 v[118:121], v[172:175], v[196:199], v[118:121]
	v_mfma_f32_16x16x32_bf16 v[110:113], v[142:145], v[204:207], v[110:113]
	v_mfma_f32_16x16x32_bf16 v[102:105], v[172:175], v[204:207], v[102:105]
	v_mfma_f32_16x16x32_bf16 v[94:97], v[142:145], v[236:239], v[94:97]
	v_mfma_f32_16x16x32_bf16 v[86:89], v[172:175], v[236:239], v[86:89]
	v_mfma_f32_16x16x32_bf16 v[78:81], v[142:145], v[244:247], v[78:81]
	v_mfma_f32_16x16x32_bf16 v[70:73], v[172:175], v[244:247], v[70:73]
	v_mfma_f32_16x16x32_bf16 v[126:129], v[168:171], v[200:203], v[126:129]
	v_mfma_f32_16x16x32_bf16 v[118:121], v[176:179], v[200:203], v[118:121]
	v_mfma_f32_16x16x32_bf16 v[110:113], v[168:171], v[220:223], v[110:113]
	v_mfma_f32_16x16x32_bf16 v[102:105], v[176:179], v[220:223], v[102:105]
	v_mfma_f32_16x16x32_bf16 v[94:97], v[168:171], v[240:243], v[94:97]
	v_mfma_f32_16x16x32_bf16 v[86:89], v[176:179], v[240:243], v[86:89]
	v_mfma_f32_16x16x32_bf16 v[78:81], v[168:171], v[248:251], v[78:81]
	v_mfma_f32_16x16x32_bf16 v[70:73], v[176:179], v[248:251], v[70:73]
	v_mfma_f32_16x16x32_bf16 v[122:125], v[180:183], v[196:199], v[122:125]
	v_mfma_f32_16x16x32_bf16 v[114:117], v[188:191], v[196:199], v[114:117]
	v_mfma_f32_16x16x32_bf16 v[106:109], v[180:183], v[204:207], v[106:109]
	v_mfma_f32_16x16x32_bf16 v[98:101], v[188:191], v[204:207], v[98:101]
	v_mfma_f32_16x16x32_bf16 v[90:93], v[180:183], v[236:239], v[90:93]
	v_mfma_f32_16x16x32_bf16 v[82:85], v[188:191], v[236:239], v[82:85]
	v_mfma_f32_16x16x32_bf16 v[74:77], v[180:183], v[244:247], v[74:77]
	v_mfma_f32_16x16x32_bf16 v[66:69], v[188:191], v[244:247], v[66:69]
	v_mfma_f32_16x16x32_bf16 v[122:125], v[184:187], v[200:203], v[122:125]
	v_mfma_f32_16x16x32_bf16 v[114:117], v[192:195], v[200:203], v[114:117]
	v_mfma_f32_16x16x32_bf16 v[106:109], v[184:187], v[220:223], v[106:109]
	v_mfma_f32_16x16x32_bf16 v[98:101], v[192:195], v[220:223], v[98:101]
	v_mfma_f32_16x16x32_bf16 v[90:93], v[184:187], v[240:243], v[90:93]
	v_mfma_f32_16x16x32_bf16 v[82:85], v[192:195], v[240:243], v[82:85]
	v_mfma_f32_16x16x32_bf16 v[74:77], v[184:187], v[248:251], v[74:77]
	v_mfma_f32_16x16x32_bf16 v[66:69], v[192:195], v[248:251], v[66:69]
	s_barrier
	s_add_i32 s57, s57, s44
	s_mov_b32 m0, s57
	ds_read_b128 v[196:199], v157 offset:16384
	ds_read_b128 v[200:203], v157 offset:17408
	ds_read_b128 v[204:207], v157 offset:18432
	ds_read_b128 v[220:223], v157 offset:19456
	global_load_lds_dwordx4 v134, s[34:35]
	s_add_i32 m0, s57, 0x2000
	s_add_u32 s58, s34, 0x40000
	s_addc_u32 s59, s35, 0
	s_add_i32 s57, s60, s44
	global_load_lds_dwordx4 v130, s[34:35]
	s_mov_b32 m0, s57
	ds_read_b128 v[236:239], v157 offset:20480
	global_load_lds_dwordx4 v134, s[58:59]
	s_add_i32 m0, s57, 0x2000
	ds_read_b128 v[240:243], v157 offset:21504
	global_load_lds_dwordx4 v130, s[58:59]
	s_mov_b32 m0, s48
	ds_read_b128 v[244:247], v157 offset:22528
	global_load_lds_dwordx4 v136, s[36:37]
	s_mov_b32 m0, s49
	ds_read_b128 v[248:251], v157 offset:23552
	global_load_lds_dwordx4 v132, s[36:37]
	s_nop 0
	s_nop 0
	s_nop 0
	s_waitcnt vmcnt(8)
	s_waitcnt lgkmcnt(0)
	s_barrier
	v_mfma_f32_16x16x32_bf16 v[62:65], v[142:145], v[196:199], v[62:65]
	v_mfma_f32_16x16x32_bf16 v[54:57], v[172:175], v[196:199], v[54:57]
	v_mfma_f32_16x16x32_bf16 v[46:49], v[142:145], v[204:207], v[46:49]
	v_mfma_f32_16x16x32_bf16 v[38:41], v[172:175], v[204:207], v[38:41]
	v_mfma_f32_16x16x32_bf16 v[30:33], v[142:145], v[236:239], v[30:33]
	v_mfma_f32_16x16x32_bf16 v[22:25], v[172:175], v[236:239], v[22:25]
	v_mfma_f32_16x16x32_bf16 v[14:17], v[142:145], v[244:247], v[14:17]
	v_mfma_f32_16x16x32_bf16 v[6:9], v[172:175], v[244:247], v[6:9]
	v_mfma_f32_16x16x32_bf16 v[62:65], v[168:171], v[200:203], v[62:65]
	v_mfma_f32_16x16x32_bf16 v[54:57], v[176:179], v[200:203], v[54:57]
	v_mfma_f32_16x16x32_bf16 v[46:49], v[168:171], v[220:223], v[46:49]
	v_mfma_f32_16x16x32_bf16 v[38:41], v[176:179], v[220:223], v[38:41]
	v_mfma_f32_16x16x32_bf16 v[30:33], v[168:171], v[240:243], v[30:33]
	v_mfma_f32_16x16x32_bf16 v[22:25], v[176:179], v[240:243], v[22:25]
	v_mfma_f32_16x16x32_bf16 v[14:17], v[168:171], v[248:251], v[14:17]
	v_mfma_f32_16x16x32_bf16 v[6:9], v[176:179], v[248:251], v[6:9]
	v_mfma_f32_16x16x32_bf16 v[58:61], v[180:183], v[196:199], v[58:61]
	v_mfma_f32_16x16x32_bf16 v[50:53], v[188:191], v[196:199], v[50:53]
	v_mfma_f32_16x16x32_bf16 v[42:45], v[180:183], v[204:207], v[42:45]
	v_mfma_f32_16x16x32_bf16 v[34:37], v[188:191], v[204:207], v[34:37]
	v_mfma_f32_16x16x32_bf16 v[26:29], v[180:183], v[236:239], v[26:29]
	v_mfma_f32_16x16x32_bf16 v[18:21], v[188:191], v[236:239], v[18:21]
	v_mfma_f32_16x16x32_bf16 v[10:13], v[180:183], v[244:247], v[10:13]
	v_mfma_f32_16x16x32_bf16 v[2:5], v[188:191], v[244:247], v[2:5]
	v_mfma_f32_16x16x32_bf16 v[58:61], v[184:187], v[200:203], v[58:61]
	v_mfma_f32_16x16x32_bf16 v[50:53], v[192:195], v[200:203], v[50:53]
	v_mfma_f32_16x16x32_bf16 v[42:45], v[184:187], v[220:223], v[42:45]
	v_mfma_f32_16x16x32_bf16 v[34:37], v[192:195], v[220:223], v[34:37]
	v_mfma_f32_16x16x32_bf16 v[26:29], v[184:187], v[240:243], v[26:29]
	v_mfma_f32_16x16x32_bf16 v[18:21], v[192:195], v[240:243], v[18:21]
	v_mfma_f32_16x16x32_bf16 v[10:13], v[184:187], v[248:251], v[10:13]
	v_mfma_f32_16x16x32_bf16 v[2:5], v[192:195], v[248:251], v[2:5]
	s_barrier
	s_add_i32 s57, 0, 0x18000
	v_add_u32_e32 v164, s57, v155
	s_add_i32 s58, 0, 0x1c000
	ds_read_b128 v[142:145], v164
	ds_read_b128 v[168:171], v164 offset:1024
	ds_read_b128 v[172:175], v164 offset:2048
	ds_read_b128 v[176:179], v164 offset:3072
	v_add_u32_e32 v164, s58, v155
	ds_read_b128 v[180:183], v164
	ds_read_b128 v[184:187], v164 offset:1024
	ds_read_b128 v[188:191], v164 offset:2048
	ds_read_b128 v[192:195], v164 offset:3072
	s_add_u32 s36, s36, 0x40000
	s_addc_u32 s37, s37, 0
	s_mov_b32 m0, s50
	ds_read_b128 v[196:199], v157 offset:32768
	ds_read_b128 v[200:203], v157 offset:33792
	ds_read_b128 v[204:207], v157 offset:34816
	ds_read_b128 v[220:223], v157 offset:35840
	ds_read_b128 v[236:239], v157 offset:36864
	ds_read_b128 v[240:243], v157 offset:37888
	ds_read_b128 v[244:247], v157 offset:38912
	global_load_lds_dwordx4 v136, s[36:37]
	s_mov_b32 m0, s51
	ds_read_b128 v[248:251], v157 offset:39936
	global_load_lds_dwordx4 v132, s[36:37]
	s_branch .Lpadj_12
	s_nop 0
	s_nop 0
	s_nop 0
	s_nop 0
	s_nop 0
	s_nop 0
	s_nop 0
	s_nop 0
	s_nop 0
	s_nop 0
	s_nop 0
	s_nop 0
.Lpadj_12:
	s_waitcnt vmcnt(8)
	s_waitcnt lgkmcnt(0)
	s_barrier
	v_mfma_f32_16x16x32_bf16 v[126:129], v[142:145], v[196:199], v[126:129]
	v_mfma_f32_16x16x32_bf16 v[118:121], v[172:175], v[196:199], v[118:121]
	v_mfma_f32_16x16x32_bf16 v[110:113], v[142:145], v[204:207], v[110:113]
	v_mfma_f32_16x16x32_bf16 v[102:105], v[172:175], v[204:207], v[102:105]
	v_mfma_f32_16x16x32_bf16 v[94:97], v[142:145], v[236:239], v[94:97]
	v_mfma_f32_16x16x32_bf16 v[86:89], v[172:175], v[236:239], v[86:89]
	v_mfma_f32_16x16x32_bf16 v[78:81], v[142:145], v[244:247], v[78:81]
	v_mfma_f32_16x16x32_bf16 v[70:73], v[172:175], v[244:247], v[70:73]
	v_mfma_f32_16x16x32_bf16 v[126:129], v[168:171], v[200:203], v[126:129]
	v_mfma_f32_16x16x32_bf16 v[118:121], v[176:179], v[200:203], v[118:121]
	v_mfma_f32_16x16x32_bf16 v[110:113], v[168:171], v[220:223], v[110:113]
	v_mfma_f32_16x16x32_bf16 v[102:105], v[176:179], v[220:223], v[102:105]
	v_mfma_f32_16x16x32_bf16 v[94:97], v[168:171], v[240:243], v[94:97]
	v_mfma_f32_16x16x32_bf16 v[86:89], v[176:179], v[240:243], v[86:89]
	v_mfma_f32_16x16x32_bf16 v[78:81], v[168:171], v[248:251], v[78:81]
	v_mfma_f32_16x16x32_bf16 v[70:73], v[176:179], v[248:251], v[70:73]
	v_mfma_f32_16x16x32_bf16 v[122:125], v[180:183], v[196:199], v[122:125]
	v_mfma_f32_16x16x32_bf16 v[114:117], v[188:191], v[196:199], v[114:117]
	v_mfma_f32_16x16x32_bf16 v[106:109], v[180:183], v[204:207], v[106:109]
	v_mfma_f32_16x16x32_bf16 v[98:101], v[188:191], v[204:207], v[98:101]
	v_mfma_f32_16x16x32_bf16 v[90:93], v[180:183], v[236:239], v[90:93]
	v_mfma_f32_16x16x32_bf16 v[82:85], v[188:191], v[236:239], v[82:85]
	v_mfma_f32_16x16x32_bf16 v[74:77], v[180:183], v[244:247], v[74:77]
	v_mfma_f32_16x16x32_bf16 v[66:69], v[188:191], v[244:247], v[66:69]
	v_mfma_f32_16x16x32_bf16 v[122:125], v[184:187], v[200:203], v[122:125]
	v_mfma_f32_16x16x32_bf16 v[114:117], v[192:195], v[200:203], v[114:117]
	v_mfma_f32_16x16x32_bf16 v[106:109], v[184:187], v[220:223], v[106:109]
	v_mfma_f32_16x16x32_bf16 v[98:101], v[192:195], v[220:223], v[98:101]
	v_mfma_f32_16x16x32_bf16 v[90:93], v[184:187], v[240:243], v[90:93]
	v_mfma_f32_16x16x32_bf16 v[82:85], v[192:195], v[240:243], v[82:85]
	v_mfma_f32_16x16x32_bf16 v[74:77], v[184:187], v[248:251], v[74:77]
	v_mfma_f32_16x16x32_bf16 v[66:69], v[192:195], v[248:251], v[66:69]
	s_barrier
	s_add_u32 s100, s36, 0xfffc0080
	s_addc_u32 s101, s37, -1
	s_add_i32 s36, s57, s44
	s_add_u32 s34, s34, 0x80
	s_mov_b32 m0, s36
	s_addc_u32 s35, s35, 0
	ds_read_b128 v[196:199], v157 offset:49152
	ds_read_b128 v[200:203], v157 offset:50176
	ds_read_b128 v[204:207], v157 offset:51200
	ds_read_b128 v[220:223], v157 offset:52224
	ds_read_b128 v[236:239], v157 offset:53248
	global_load_lds_dwordx4 v134, s[34:35]
	s_add_i32 m0, s36, 0x2000
	s_add_i32 s36, s58, s44
	global_load_lds_dwordx4 v130, s[34:35]
	s_mov_b32 m0, s36
	s_add_u32 s34, s34, 0x40000
	s_addc_u32 s35, s35, 0
	global_load_lds_dwordx4 v134, s[34:35]
	s_add_i32 m0, s36, 0x2000
	ds_read_b128 v[240:243], v157 offset:54272
	global_load_lds_dwordx4 v130, s[34:35]
	s_mov_b32 m0, s52
	ds_read_b128 v[244:247], v157 offset:55296
	global_load_lds_dwordx4 v136, s[100:101]
	s_mov_b32 m0, s53
	ds_read_b128 v[248:251], v157 offset:56320
	global_load_lds_dwordx4 v132, s[100:101]
	s_branch .Lpadj_13
	s_nop 0
	s_nop 0
	s_nop 0
	s_nop 0
	s_nop 0
	s_nop 0
	s_nop 0
	s_nop 0
	s_nop 0
	s_nop 0
	s_nop 0
	s_nop 0

.LBB0_476:
	s_add_i32 s63, s31, 2
	s_add_u32 s38, s28, s36
	s_addc_u32 s39, s29, s37
	s_add_u32 s64, s26, s36
	s_addc_u32 s65, s27, s37
	s_add_i32 s66, 0, 0x10000
	s_cmp_eq_u32 s59, s31
	s_cselect_b32 s39, s9, s39
	s_cselect_b32 s38, s8, s38
	s_cselect_b32 s65, s35, s65
	s_cselect_b32 s64, s34, s64
	s_add_i32 s31, 0, 0x14000
	v_add_u32_e32 v160, s66, v146
	v_add_u32_e32 v176, s31, v146
	ds_read_b128 v[148:151], v160
	ds_read_b128 v[152:155], v160 offset:1024
	ds_read_b128 v[156:159], v160 offset:2048
	ds_read_b128 v[160:163], v160 offset:3072
	ds_read_b128 v[164:167], v176
	ds_read_b128 v[168:171], v176 offset:1024
	ds_read_b128 v[172:175], v176 offset:2048
	ds_read_b128 v[176:179], v176 offset:3072
	v_lshl_add_u64 v[208:209], s[28:29], 0, v[142:143]
	s_add_i32 m0, s51, 0xc000
	ds_read_b128 v[180:183], v147
	ds_read_b128 v[184:187], v147 offset:1024
	ds_read_b128 v[188:191], v147 offset:2048
	ds_read_b128 v[192:195], v147 offset:3072
	ds_read_b128 v[196:199], v147 offset:4096
	ds_read_b128 v[200:203], v147 offset:5120
	ds_read_b128 v[204:207], v147 offset:6144
	global_load_lds_dwordx4 v[208:209], off
	v_lshl_add_u64 v[208:209], s[28:29], 0, v[144:145]
	s_add_i32 m0, s51, 0xe000
	ds_read_b128 v[220:223], v147 offset:7168
	global_load_lds_dwordx4 v[208:209], off
	s_branch .Lpadj_14
	s_nop 0
	s_nop 0
	s_nop 0
	s_nop 0
	s_nop 0
	s_nop 0
	s_nop 0
	s_nop 0
	s_nop 0
	s_nop 0
	s_nop 0
.Lpadj_14:
	s_waitcnt vmcnt(8)
	s_waitcnt lgkmcnt(0)
	s_barrier
	v_mfma_f32_16x16x32_bf16 v[126:129], v[148:151], v[180:183], v[126:129]
	v_mfma_f32_16x16x32_bf16 v[122:125], v[156:159], v[180:183], v[122:125]
	v_mfma_f32_16x16x32_bf16 v[110:113], v[148:151], v[188:191], v[110:113]
	v_mfma_f32_16x16x32_bf16 v[106:109], v[156:159], v[188:191], v[106:109]
	v_mfma_f32_16x16x32_bf16 v[94:97], v[148:151], v[196:199], v[94:97]
	v_mfma_f32_16x16x32_bf16 v[90:93], v[156:159], v[196:199], v[90:93]
	v_mfma_f32_16x16x32_bf16 v[78:81], v[148:151], v[204:207], v[78:81]
	v_mfma_f32_16x16x32_bf16 v[74:77], v[156:159], v[204:207], v[74:77]
	v_mfma_f32_16x16x32_bf16 v[126:129], v[152:155], v[184:187], v[126:129]
	v_mfma_f32_16x16x32_bf16 v[122:125], v[160:163], v[184:187], v[122:125]
	v_mfma_f32_16x16x32_bf16 v[110:113], v[152:155], v[192:195], v[110:113]
	v_mfma_f32_16x16x32_bf16 v[106:109], v[160:163], v[192:195], v[106:109]
	v_mfma_f32_16x16x32_bf16 v[94:97], v[152:155], v[200:203], v[94:97]
	v_mfma_f32_16x16x32_bf16 v[90:93], v[160:163], v[200:203], v[90:93]
	v_mfma_f32_16x16x32_bf16 v[78:81], v[152:155], v[220:223], v[78:81]
	v_mfma_f32_16x16x32_bf16 v[74:77], v[160:163], v[220:223], v[74:77]
	v_mfma_f32_16x16x32_bf16 v[118:121], v[164:167], v[180:183], v[118:121]
	v_mfma_f32_16x16x32_bf16 v[114:117], v[172:175], v[180:183], v[114:117]
	v_mfma_f32_16x16x32_bf16 v[102:105], v[164:167], v[188:191], v[102:105]
	v_mfma_f32_16x16x32_bf16 v[98:101], v[172:175], v[188:191], v[98:101]
	v_mfma_f32_16x16x32_bf16 v[86:89], v[164:167], v[196:199], v[86:89]
	v_mfma_f32_16x16x32_bf16 v[82:85], v[172:175], v[196:199], v[82:85]
	v_mfma_f32_16x16x32_bf16 v[70:73], v[164:167], v[204:207], v[70:73]
	v_mfma_f32_16x16x32_bf16 v[66:69], v[172:175], v[204:207], v[66:69]
	v_mfma_f32_16x16x32_bf16 v[118:121], v[168:171], v[184:187], v[118:121]
	v_mfma_f32_16x16x32_bf16 v[114:117], v[176:179], v[184:187], v[114:117]
	v_mfma_f32_16x16x32_bf16 v[102:105], v[168:171], v[192:195], v[102:105]
	v_mfma_f32_16x16x32_bf16 v[98:101], v[176:179], v[192:195], v[98:101]
	v_mfma_f32_16x16x32_bf16 v[86:89], v[168:171], v[200:203], v[86:89]
	v_mfma_f32_16x16x32_bf16 v[82:85], v[176:179], v[200:203], v[82:85]
	v_mfma_f32_16x16x32_bf16 v[70:73], v[168:171], v[220:223], v[70:73]
	v_mfma_f32_16x16x32_bf16 v[66:69], v[176:179], v[220:223], v[66:69]
	s_barrier
	s_add_i32 s66, s66, s47
	s_mov_b32 m0, s66
	ds_read_b128 v[180:183], v147 offset:16384
	ds_read_b128 v[184:187], v147 offset:17408
	ds_read_b128 v[188:191], v147 offset:18432
	ds_read_b128 v[192:195], v147 offset:19456
	global_load_lds_dwordx4 v132, s[64:65]
	s_add_i32 m0, s66, 0x2000
	s_mov_b64 s[100:101], s[64:65]
	s_add_u32 s64, s64, s45
	s_addc_u32 s65, s65, 0
	s_add_i32 s31, s31, s47
	global_load_lds_dwordx4 v136, s[100:101]
	s_mov_b32 m0, s31
	ds_read_b128 v[196:199], v147 offset:20480
	global_load_lds_dwordx4 v132, s[64:65]
	s_add_i32 m0, s31, 0x2000
	ds_read_b128 v[200:203], v147 offset:21504
	global_load_lds_dwordx4 v136, s[64:65]
	s_mov_b32 m0, s51
	ds_read_b128 v[204:207], v147 offset:22528
	global_load_lds_dwordx4 v130, s[38:39]
	s_mov_b32 m0, s52
	ds_read_b128 v[220:223], v147 offset:23552
	global_load_lds_dwordx4 v134, s[38:39]
	s_nop 0
	s_nop 0
	s_nop 0
	s_waitcnt vmcnt(8)
	s_waitcnt lgkmcnt(0)
	s_barrier
	v_mfma_f32_16x16x32_bf16 v[62:65], v[148:151], v[180:183], v[62:65]
	v_mfma_f32_16x16x32_bf16 v[58:61], v[156:159], v[180:183], v[58:61]
	v_mfma_f32_16x16x32_bf16 v[46:49], v[148:151], v[188:191], v[46:49]
	v_mfma_f32_16x16x32_bf16 v[42:45], v[156:159], v[188:191], v[42:45]
	v_mfma_f32_16x16x32_bf16 v[30:33], v[148:151], v[196:199], v[30:33]
	v_mfma_f32_16x16x32_bf16 v[26:29], v[156:159], v[196:199], v[26:29]
	v_mfma_f32_16x16x32_bf16 v[14:17], v[148:151], v[204:207], v[14:17]
	v_mfma_f32_16x16x32_bf16 v[10:13], v[156:159], v[204:207], v[10:13]
	v_mfma_f32_16x16x32_bf16 v[62:65], v[152:155], v[184:187], v[62:65]
	v_mfma_f32_16x16x32_bf16 v[58:61], v[160:163], v[184:187], v[58:61]
	v_mfma_f32_16x16x32_bf16 v[46:49], v[152:155], v[192:195], v[46:49]
	v_mfma_f32_16x16x32_bf16 v[42:45], v[160:163], v[192:195], v[42:45]
	v_mfma_f32_16x16x32_bf16 v[30:33], v[152:155], v[200:203], v[30:33]
	v_mfma_f32_16x16x32_bf16 v[26:29], v[160:163], v[200:203], v[26:29]
	v_mfma_f32_16x16x32_bf16 v[14:17], v[152:155], v[220:223], v[14:17]
	v_mfma_f32_16x16x32_bf16 v[10:13], v[160:163], v[220:223], v[10:13]
	v_mfma_f32_16x16x32_bf16 v[54:57], v[164:167], v[180:183], v[54:57]
	v_mfma_f32_16x16x32_bf16 v[50:53], v[172:175], v[180:183], v[50:53]
	v_mfma_f32_16x16x32_bf16 v[38:41], v[164:167], v[188:191], v[38:41]
	v_mfma_f32_16x16x32_bf16 v[34:37], v[172:175], v[188:191], v[34:37]
	v_mfma_f32_16x16x32_bf16 v[22:25], v[164:167], v[196:199], v[22:25]
	v_mfma_f32_16x16x32_bf16 v[18:21], v[172:175], v[196:199], v[18:21]
	v_mfma_f32_16x16x32_bf16 v[6:9], v[164:167], v[204:207], v[6:9]
	v_mfma_f32_16x16x32_bf16 v[2:5], v[172:175], v[204:207], v[2:5]
	v_mfma_f32_16x16x32_bf16 v[54:57], v[168:171], v[184:187], v[54:57]
	v_mfma_f32_16x16x32_bf16 v[50:53], v[176:179], v[184:187], v[50:53]
	v_mfma_f32_16x16x32_bf16 v[38:41], v[168:171], v[192:195], v[38:41]
	v_mfma_f32_16x16x32_bf16 v[34:37], v[176:179], v[192:195], v[34:37]
	v_mfma_f32_16x16x32_bf16 v[22:25], v[168:171], v[200:203], v[22:25]
	v_mfma_f32_16x16x32_bf16 v[18:21], v[176:179], v[200:203], v[18:21]
	v_mfma_f32_16x16x32_bf16 v[6:9], v[168:171], v[220:223], v[6:9]
	v_mfma_f32_16x16x32_bf16 v[2:5], v[176:179], v[220:223], v[2:5]
	s_barrier
	s_add_i32 s31, 0, 0x18000
	s_add_i32 s64, 0, 0x1c000
	v_add_u32_e32 v160, s31, v146
	v_add_u32_e32 v176, s64, v146
	ds_read_b128 v[148:151], v160
	ds_read_b128 v[152:155], v160 offset:1024
	ds_read_b128 v[156:159], v160 offset:2048
	ds_read_b128 v[160:163], v160 offset:3072
	ds_read_b128 v[164:167], v176
	ds_read_b128 v[168:171], v176 offset:1024
	ds_read_b128 v[172:175], v176 offset:2048
	ds_read_b128 v[176:179], v176 offset:3072
	s_add_u32 s38, s38, s45
	s_addc_u32 s39, s39, 0
	s_mov_b32 m0, s53
	ds_read_b128 v[180:183], v147 offset:32768
	ds_read_b128 v[184:187], v147 offset:33792
	ds_read_b128 v[188:191], v147 offset:34816
	ds_read_b128 v[192:195], v147 offset:35840
	ds_read_b128 v[196:199], v147 offset:36864
	ds_read_b128 v[200:203], v147 offset:37888
	ds_read_b128 v[204:207], v147 offset:38912
	global_load_lds_dwordx4 v130, s[38:39]
	s_mov_b32 m0, s54
	ds_read_b128 v[220:223], v147 offset:39936
	global_load_lds_dwordx4 v134, s[38:39]
	s_branch .Lpadj_15
	s_nop 0
	s_nop 0
	s_nop 0
	s_nop 0
	s_nop 0
	s_nop 0
	s_nop 0
	s_nop 0
	s_nop 0
	s_nop 0
	s_nop 0
	s_nop 0
	s_nop 0
.Lpadj_15:
	s_waitcnt vmcnt(8)
	s_waitcnt lgkmcnt(0)
	s_barrier
	v_mfma_f32_16x16x32_bf16 v[126:129], v[148:151], v[180:183], v[126:129]
	v_mfma_f32_16x16x32_bf16 v[122:125], v[156:159], v[180:183], v[122:125]
	v_mfma_f32_16x16x32_bf16 v[110:113], v[148:151], v[188:191], v[110:113]
	v_mfma_f32_16x16x32_bf16 v[106:109], v[156:159], v[188:191], v[106:109]
	v_mfma_f32_16x16x32_bf16 v[94:97], v[148:151], v[196:199], v[94:97]
	v_mfma_f32_16x16x32_bf16 v[90:93], v[156:159], v[196:199], v[90:93]
	v_mfma_f32_16x16x32_bf16 v[78:81], v[148:151], v[204:207], v[78:81]
	v_mfma_f32_16x16x32_bf16 v[74:77], v[156:159], v[204:207], v[74:77]
	v_mfma_f32_16x16x32_bf16 v[126:129], v[152:155], v[184:187], v[126:129]
	v_mfma_f32_16x16x32_bf16 v[122:125], v[160:163], v[184:187], v[122:125]
	v_mfma_f32_16x16x32_bf16 v[110:113], v[152:155], v[192:195], v[110:113]
	v_mfma_f32_16x16x32_bf16 v[106:109], v[160:163], v[192:195], v[106:109]
	v_mfma_f32_16x16x32_bf16 v[94:97], v[152:155], v[200:203], v[94:97]
	v_mfma_f32_16x16x32_bf16 v[90:93], v[160:163], v[200:203], v[90:93]
	v_mfma_f32_16x16x32_bf16 v[78:81], v[152:155], v[220:223], v[78:81]
	v_mfma_f32_16x16x32_bf16 v[74:77], v[160:163], v[220:223], v[74:77]
	v_mfma_f32_16x16x32_bf16 v[118:121], v[164:167], v[180:183], v[118:121]
	v_mfma_f32_16x16x32_bf16 v[114:117], v[172:175], v[180:183], v[114:117]
	v_mfma_f32_16x16x32_bf16 v[102:105], v[164:167], v[188:191], v[102:105]
	v_mfma_f32_16x16x32_bf16 v[98:101], v[172:175], v[188:191], v[98:101]
	v_mfma_f32_16x16x32_bf16 v[86:89], v[164:167], v[196:199], v[86:89]
	v_mfma_f32_16x16x32_bf16 v[82:85], v[172:175], v[196:199], v[82:85]
	v_mfma_f32_16x16x32_bf16 v[70:73], v[164:167], v[204:207], v[70:73]
	v_mfma_f32_16x16x32_bf16 v[66:69], v[172:175], v[204:207], v[66:69]
	v_mfma_f32_16x16x32_bf16 v[118:121], v[168:171], v[184:187], v[118:121]
	v_mfma_f32_16x16x32_bf16 v[114:117], v[176:179], v[184:187], v[114:117]
	v_mfma_f32_16x16x32_bf16 v[102:105], v[168:171], v[192:195], v[102:105]
	v_mfma_f32_16x16x32_bf16 v[98:101], v[176:179], v[192:195], v[98:101]
	v_mfma_f32_16x16x32_bf16 v[86:89], v[168:171], v[200:203], v[86:89]
	v_mfma_f32_16x16x32_bf16 v[82:85], v[176:179], v[200:203], v[82:85]
	v_mfma_f32_16x16x32_bf16 v[70:73], v[168:171], v[220:223], v[70:73]
	v_mfma_f32_16x16x32_bf16 v[66:69], v[176:179], v[220:223], v[66:69]
	s_barrier
	s_add_i32 s31, s31, s47
	s_add_u32 s100, s100, 0x80
	s_addc_u32 s101, s101, 0
	s_mov_b32 m0, s31
	ds_read_b128 v[180:183], v147 offset:49152
	ds_read_b128 v[184:187], v147 offset:50176
	ds_read_b128 v[188:191], v147 offset:51200
	ds_read_b128 v[192:195], v147 offset:52224
	global_load_lds_dwordx4 v132, s[100:101]
	s_add_i32 m0, s31, 0x2000
	s_add_i32 s31, s64, s47
	global_load_lds_dwordx4 v136, s[100:101]
	s_add_u32 s100, s100, s45
	s_addc_u32 s101, s101, 0
	s_mov_b32 m0, s31
	ds_read_b128 v[196:199], v147 offset:53248
	global_load_lds_dwordx4 v132, s[100:101]
	s_add_i32 m0, s31, 0x2000
	ds_read_b128 v[200:203], v147 offset:54272
	global_load_lds_dwordx4 v136, s[100:101]
	s_sub_u32 s38, s38, s45
	s_subb_u32 s39, s39, 0
	s_add_u32 s38, s38, 0x80
	s_addc_u32 s39, s39, 0
	s_mov_b32 m0, s57
	ds_read_b128 v[204:207], v147 offset:55296
	global_load_lds_dwordx4 v130, s[38:39]
	s_mov_b32 m0, s58
	ds_read_b128 v[220:223], v147 offset:56320
	global_load_lds_dwordx4 v134, s[38:39]
	s_branch .Lpadj_16
	s_nop 0
	s_nop 0
	s_nop 0
	s_nop 0
	s_nop 0
	s_nop 0
	s_nop 0
	s_nop 0
	s_nop 0
	s_nop 0
	s_nop 0

.LBB0_640:
	s_add_u32 s22, s20, 0xfffc0080
	s_addc_u32 s23, s21, -1
	s_add_i32 s46, 0, 0x10000
	s_cmp_eq_u32 s45, 12
	s_cselect_b32 s25, s13, s23
	s_cselect_b32 s24, s19, s22
	v_add_u32_e32 v150, s46, v159
	s_cselect_b32 s23, s11, s44
	s_cselect_b32 s22, s41, s43
	s_add_i32 s48, 0, 0x14000
	ds_read_b128 v[164:167], v150
	ds_read_b128 v[168:171], v150 offset:1024
	ds_read_b128 v[172:175], v150 offset:2048
	ds_read_b128 v[176:179], v150 offset:3072
	v_add_u32_e32 v150, s48, v159
	ds_read_b128 v[180:183], v150
	ds_read_b128 v[184:187], v150 offset:1024
	ds_read_b128 v[188:191], v150 offset:2048
	ds_read_b128 v[192:195], v150 offset:3072
	s_add_i32 m0, s30, 0xc000
	ds_read_b128 v[196:199], v162
	ds_read_b128 v[200:203], v162 offset:1024
	ds_read_b128 v[204:207], v162 offset:2048
	ds_read_b128 v[220:223], v162 offset:3072
	ds_read_b128 v[236:239], v162 offset:4096
	ds_read_b128 v[240:243], v162 offset:5120
	ds_read_b128 v[244:247], v162 offset:6144
	global_load_lds_dwordx4 v140, s[20:21]
	s_add_i32 m0, s30, 0xe000
	ds_read_b128 v[248:251], v162 offset:7168
	global_load_lds_dwordx4 v138, s[20:21]
	s_branch .Lpadj_21
	s_nop 0
	s_nop 0
	s_nop 0
	s_nop 0
	s_nop 0
	s_nop 0
	s_nop 0
	s_nop 0
	s_nop 0
	s_nop 0
	s_nop 0
	s_nop 0
	s_nop 0
.Lpadj_21:
	s_waitcnt vmcnt(8)
	s_waitcnt lgkmcnt(0)
	s_barrier
	v_mfma_f32_16x16x32_bf16 v[126:129], v[164:167], v[196:199], v[126:129]
	v_mfma_f32_16x16x32_bf16 v[122:125], v[172:175], v[196:199], v[122:125]
	v_mfma_f32_16x16x32_bf16 v[118:121], v[164:167], v[204:207], v[118:121]
	v_mfma_f32_16x16x32_bf16 v[114:117], v[172:175], v[204:207], v[114:117]
	v_mfma_f32_16x16x32_bf16 v[110:113], v[164:167], v[236:239], v[110:113]
	v_mfma_f32_16x16x32_bf16 v[106:109], v[172:175], v[236:239], v[106:109]
	v_mfma_f32_16x16x32_bf16 v[102:105], v[164:167], v[244:247], v[102:105]
	v_mfma_f32_16x16x32_bf16 v[98:101], v[172:175], v[244:247], v[98:101]
	v_mfma_f32_16x16x32_bf16 v[126:129], v[168:171], v[200:203], v[126:129]
	v_mfma_f32_16x16x32_bf16 v[122:125], v[176:179], v[200:203], v[122:125]
	v_mfma_f32_16x16x32_bf16 v[118:121], v[168:171], v[220:223], v[118:121]
	v_mfma_f32_16x16x32_bf16 v[114:117], v[176:179], v[220:223], v[114:117]
	v_mfma_f32_16x16x32_bf16 v[110:113], v[168:171], v[240:243], v[110:113]
	v_mfma_f32_16x16x32_bf16 v[106:109], v[176:179], v[240:243], v[106:109]
	v_mfma_f32_16x16x32_bf16 v[102:105], v[168:171], v[248:251], v[102:105]
	v_mfma_f32_16x16x32_bf16 v[98:101], v[176:179], v[248:251], v[98:101]
	v_mfma_f32_16x16x32_bf16 v[94:97], v[180:183], v[196:199], v[94:97]
	v_mfma_f32_16x16x32_bf16 v[90:93], v[188:191], v[196:199], v[90:93]
	v_mfma_f32_16x16x32_bf16 v[86:89], v[180:183], v[204:207], v[86:89]
	v_mfma_f32_16x16x32_bf16 v[82:85], v[188:191], v[204:207], v[82:85]
	v_mfma_f32_16x16x32_bf16 v[78:81], v[180:183], v[236:239], v[78:81]
	v_mfma_f32_16x16x32_bf16 v[74:77], v[188:191], v[236:239], v[74:77]
	v_mfma_f32_16x16x32_bf16 v[70:73], v[180:183], v[244:247], v[70:73]
	v_mfma_f32_16x16x32_bf16 v[66:69], v[188:191], v[244:247], v[66:69]
	v_mfma_f32_16x16x32_bf16 v[94:97], v[184:187], v[200:203], v[94:97]
	v_mfma_f32_16x16x32_bf16 v[90:93], v[192:195], v[200:203], v[90:93]
	v_mfma_f32_16x16x32_bf16 v[86:89], v[184:187], v[220:223], v[86:89]
	v_mfma_f32_16x16x32_bf16 v[82:85], v[192:195], v[220:223], v[82:85]
	v_mfma_f32_16x16x32_bf16 v[78:81], v[184:187], v[240:243], v[78:81]
	v_mfma_f32_16x16x32_bf16 v[74:77], v[192:195], v[240:243], v[74:77]
	v_mfma_f32_16x16x32_bf16 v[70:73], v[184:187], v[248:251], v[70:73]
	v_mfma_f32_16x16x32_bf16 v[66:69], v[192:195], v[248:251], v[66:69]
	s_barrier
	s_add_i32 s46, s46, s28
	s_mov_b32 m0, s46
	ds_read_b128 v[196:199], v162 offset:16384
	ds_read_b128 v[200:203], v162 offset:17408
	ds_read_b128 v[204:207], v162 offset:18432
	ds_read_b128 v[220:223], v162 offset:19456
	global_load_lds_dwordx4 v134, s[22:23]
	s_add_i32 m0, s46, 0x2000
	s_add_u32 s46, s22, 0x40000
	s_addc_u32 s47, s23, 0
	s_add_i32 s48, s48, s28
	global_load_lds_dwordx4 v130, s[22:23]
	s_mov_b32 m0, s48
	ds_read_b128 v[236:239], v162 offset:20480
	global_load_lds_dwordx4 v134, s[46:47]
	s_add_i32 m0, s48, 0x2000
	ds_read_b128 v[240:243], v162 offset:21504
	global_load_lds_dwordx4 v130, s[46:47]
	s_mov_b32 m0, s30
	ds_read_b128 v[244:247], v162 offset:22528
	global_load_lds_dwordx4 v136, s[24:25]
	s_mov_b32 m0, s31
	ds_read_b128 v[248:251], v162 offset:23552
	global_load_lds_dwordx4 v132, s[24:25]
	s_nop 0
	s_nop 0
	s_nop 0
	s_waitcnt vmcnt(8)
	s_waitcnt lgkmcnt(0)
	s_barrier
	v_mfma_f32_16x16x32_bf16 v[62:65], v[164:167], v[196:199], v[62:65]
	v_mfma_f32_16x16x32_bf16 v[58:61], v[172:175], v[196:199], v[58:61]
	v_mfma_f32_16x16x32_bf16 v[54:57], v[164:167], v[204:207], v[54:57]
	v_mfma_f32_16x16x32_bf16 v[50:53], v[172:175], v[204:207], v[50:53]
	v_mfma_f32_16x16x32_bf16 v[46:49], v[164:167], v[236:239], v[46:49]
	v_mfma_f32_16x16x32_bf16 v[42:45], v[172:175], v[236:239], v[42:45]
	v_mfma_f32_16x16x32_bf16 v[38:41], v[164:167], v[244:247], v[38:41]
	v_mfma_f32_16x16x32_bf16 v[34:37], v[172:175], v[244:247], v[34:37]
	v_mfma_f32_16x16x32_bf16 v[62:65], v[168:171], v[200:203], v[62:65]
	v_mfma_f32_16x16x32_bf16 v[58:61], v[176:179], v[200:203], v[58:61]
	v_mfma_f32_16x16x32_bf16 v[54:57], v[168:171], v[220:223], v[54:57]
	v_mfma_f32_16x16x32_bf16 v[50:53], v[176:179], v[220:223], v[50:53]
	v_mfma_f32_16x16x32_bf16 v[46:49], v[168:171], v[240:243], v[46:49]
	v_mfma_f32_16x16x32_bf16 v[42:45], v[176:179], v[240:243], v[42:45]
	v_mfma_f32_16x16x32_bf16 v[38:41], v[168:171], v[248:251], v[38:41]
	v_mfma_f32_16x16x32_bf16 v[34:37], v[176:179], v[248:251], v[34:37]
	v_mfma_f32_16x16x32_bf16 v[30:33], v[180:183], v[196:199], v[30:33]
	v_mfma_f32_16x16x32_bf16 v[26:29], v[188:191], v[196:199], v[26:29]
	v_mfma_f32_16x16x32_bf16 v[22:25], v[180:183], v[204:207], v[22:25]
	v_mfma_f32_16x16x32_bf16 v[18:21], v[188:191], v[204:207], v[18:21]
	v_mfma_f32_16x16x32_bf16 v[14:17], v[180:183], v[236:239], v[14:17]
	v_mfma_f32_16x16x32_bf16 v[10:13], v[188:191], v[236:239], v[10:13]
	v_mfma_f32_16x16x32_bf16 v[6:9], v[180:183], v[244:247], v[6:9]
	v_mfma_f32_16x16x32_bf16 v[2:5], v[188:191], v[244:247], v[2:5]
	v_mfma_f32_16x16x32_bf16 v[30:33], v[184:187], v[200:203], v[30:33]
	v_mfma_f32_16x16x32_bf16 v[26:29], v[192:195], v[200:203], v[26:29]
	v_mfma_f32_16x16x32_bf16 v[22:25], v[184:187], v[220:223], v[22:25]
	v_mfma_f32_16x16x32_bf16 v[18:21], v[192:195], v[220:223], v[18:21]
	v_mfma_f32_16x16x32_bf16 v[14:17], v[184:187], v[240:243], v[14:17]
	v_mfma_f32_16x16x32_bf16 v[10:13], v[192:195], v[240:243], v[10:13]
	v_mfma_f32_16x16x32_bf16 v[6:9], v[184:187], v[248:251], v[6:9]
	v_mfma_f32_16x16x32_bf16 v[2:5], v[192:195], v[248:251], v[2:5]
	s_barrier
	s_add_i32 s46, 0, 0x18000
	v_add_u32_e32 v163, s46, v159
	s_add_i32 s47, 0, 0x1c000
	ds_read_b128 v[164:167], v163
	ds_read_b128 v[168:171], v163 offset:1024
	ds_read_b128 v[172:175], v163 offset:2048
	ds_read_b128 v[176:179], v163 offset:3072
	v_add_u32_e32 v163, s47, v159
	ds_read_b128 v[180:183], v163
	ds_read_b128 v[184:187], v163 offset:1024
	ds_read_b128 v[188:191], v163 offset:2048
	ds_read_b128 v[192:195], v163 offset:3072
	s_add_u32 s24, s24, 0x40000
	s_addc_u32 s25, s25, 0
	s_mov_b32 m0, s34
	ds_read_b128 v[196:199], v162 offset:32768
	ds_read_b128 v[200:203], v162 offset:33792
	ds_read_b128 v[204:207], v162 offset:34816
	ds_read_b128 v[220:223], v162 offset:35840
	ds_read_b128 v[236:239], v162 offset:36864
	ds_read_b128 v[240:243], v162 offset:37888
	ds_read_b128 v[244:247], v162 offset:38912
	global_load_lds_dwordx4 v136, s[24:25]
	s_mov_b32 m0, s35
	ds_read_b128 v[248:251], v162 offset:39936
	global_load_lds_dwordx4 v132, s[24:25]
	s_branch .Lpadj_22
	s_nop 0
	s_nop 0
	s_nop 0
	s_nop 0
	s_nop 0
	s_nop 0
	s_nop 0
	s_nop 0
	s_nop 0
	s_nop 0
	s_nop 0
	s_nop 0
.Lpadj_22:
	s_waitcnt vmcnt(8)
	s_waitcnt lgkmcnt(0)
	s_barrier
	v_mfma_f32_16x16x32_bf16 v[126:129], v[164:167], v[196:199], v[126:129]
	v_mfma_f32_16x16x32_bf16 v[122:125], v[172:175], v[196:199], v[122:125]
	v_mfma_f32_16x16x32_bf16 v[118:121], v[164:167], v[204:207], v[118:121]
	v_mfma_f32_16x16x32_bf16 v[114:117], v[172:175], v[204:207], v[114:117]
	v_mfma_f32_16x16x32_bf16 v[110:113], v[164:167], v[236:239], v[110:113]
	v_mfma_f32_16x16x32_bf16 v[106:109], v[172:175], v[236:239], v[106:109]
	v_mfma_f32_16x16x32_bf16 v[102:105], v[164:167], v[244:247], v[102:105]
	v_mfma_f32_16x16x32_bf16 v[98:101], v[172:175], v[244:247], v[98:101]
	v_mfma_f32_16x16x32_bf16 v[126:129], v[168:171], v[200:203], v[126:129]
	v_mfma_f32_16x16x32_bf16 v[122:125], v[176:179], v[200:203], v[122:125]
	v_mfma_f32_16x16x32_bf16 v[118:121], v[168:171], v[220:223], v[118:121]
	v_mfma_f32_16x16x32_bf16 v[114:117], v[176:179], v[220:223], v[114:117]
	v_mfma_f32_16x16x32_bf16 v[110:113], v[168:171], v[240:243], v[110:113]
	v_mfma_f32_16x16x32_bf16 v[106:109], v[176:179], v[240:243], v[106:109]
	v_mfma_f32_16x16x32_bf16 v[102:105], v[168:171], v[248:251], v[102:105]
	v_mfma_f32_16x16x32_bf16 v[98:101], v[176:179], v[248:251], v[98:101]
	v_mfma_f32_16x16x32_bf16 v[94:97], v[180:183], v[196:199], v[94:97]
	v_mfma_f32_16x16x32_bf16 v[90:93], v[188:191], v[196:199], v[90:93]
	v_mfma_f32_16x16x32_bf16 v[86:89], v[180:183], v[204:207], v[86:89]
	v_mfma_f32_16x16x32_bf16 v[82:85], v[188:191], v[204:207], v[82:85]
	v_mfma_f32_16x16x32_bf16 v[78:81], v[180:183], v[236:239], v[78:81]
	v_mfma_f32_16x16x32_bf16 v[74:77], v[188:191], v[236:239], v[74:77]
	v_mfma_f32_16x16x32_bf16 v[70:73], v[180:183], v[244:247], v[70:73]
	v_mfma_f32_16x16x32_bf16 v[66:69], v[188:191], v[244:247], v[66:69]
	v_mfma_f32_16x16x32_bf16 v[94:97], v[184:187], v[200:203], v[94:97]
	v_mfma_f32_16x16x32_bf16 v[90:93], v[192:195], v[200:203], v[90:93]
	v_mfma_f32_16x16x32_bf16 v[86:89], v[184:187], v[220:223], v[86:89]
	v_mfma_f32_16x16x32_bf16 v[82:85], v[192:195], v[220:223], v[82:85]
	v_mfma_f32_16x16x32_bf16 v[78:81], v[184:187], v[240:243], v[78:81]
	v_mfma_f32_16x16x32_bf16 v[74:77], v[192:195], v[240:243], v[74:77]
	v_mfma_f32_16x16x32_bf16 v[70:73], v[184:187], v[248:251], v[70:73]
	v_mfma_f32_16x16x32_bf16 v[66:69], v[192:195], v[248:251], v[66:69]
	s_barrier
	s_add_u32 s100, s24, 0xfffc0080
	s_addc_u32 s101, s25, -1
	s_add_u32 s22, s22, 0x80
	s_addc_u32 s23, s23, 0
	s_add_i32 s24, s46, s28
	s_mov_b32 m0, s24
	ds_read_b128 v[196:199], v162 offset:49152
	ds_read_b128 v[200:203], v162 offset:50176
	ds_read_b128 v[204:207], v162 offset:51200
	ds_read_b128 v[220:223], v162 offset:52224
	global_load_lds_dwordx4 v134, s[22:23]
	s_add_i32 m0, s24, 0x2000
	s_add_i32 s24, s47, s28
	global_load_lds_dwordx4 v130, s[22:23]
	s_add_u32 s22, s22, 0x40000
	s_addc_u32 s23, s23, 0
	s_mov_b32 m0, s24
	ds_read_b128 v[236:239], v162 offset:53248
	global_load_lds_dwordx4 v134, s[22:23]
	s_add_i32 m0, s24, 0x2000
	ds_read_b128 v[240:243], v162 offset:54272
	global_load_lds_dwordx4 v130, s[22:23]
	s_mov_b32 m0, s36
	ds_read_b128 v[244:247], v162 offset:55296
	global_load_lds_dwordx4 v136, s[100:101]
	s_mov_b32 m0, s37
	ds_read_b128 v[248:251], v162 offset:56320
	global_load_lds_dwordx4 v132, s[100:101]
	s_branch .Lpadj_23
	s_nop 0
	s_nop 0
	s_nop 0
	s_nop 0
	s_nop 0
	s_nop 0
	s_nop 0
	s_nop 0
	s_nop 0
	s_nop 0
	s_nop 0
	s_nop 0
